# top-level barrier word replicated 8x, each workgroup polls the copy of its own XCD
# speedup vs baseline: 1.0302x; 1.0029x over previous
; __device__ __forceinline__ unsigned xb_ld(unsigned* p)              { return __hip_atomic_load(p, __ATOMIC_RELAXED, __HIP_MEMORY_SCOPE_AGENT); }
; #define XB_SPIN(cond, bar) do { unsigned _sp = 0; while (cond) { __builtin_amdgcn_s_sleep(1); \
;     if ((++_sp & 255u) == 0u) { if (xb_ld(&(bar)[XB_TMO])) break; if (_sp > XB_SPIN_CAP) { atomicAdd(&(bar)[XB_TMO], 1u); break; } } } } while (0)
; __device__ __forceinline__ void xcd_barrier(const XcdBarrier& b) {
;     ...
;         XB_SPIN((int)(xb_ld(&bar[XB_TOP]) - target) < 0, bar);
;         asm volatile("s_waitcnt vmcnt(0)" ::: "memory");
;         b.st[2] = target;
.LBB0_8:
	s_or_b64 exec, exec, s[16:17]
	v_readlane_b32 s4, v253, 29
	v_readfirstlane_b32 s101, v0
	s_nop 1
	v_mov_b32_e32 v1, s4
	ds_write_b32 v1, v0
	v_readlane_b32 vcc_lo, v253, 24
	v_mov_b32_e32 v251, 0
	s_nop 1
	s_and_b32 vcc_lo, vcc_lo, 0x700
	v_mov_b32_e32 v250, vcc_lo
	v_add_u32_e32 v250, 0x3400, v250
	v_lshl_add_u64 v[248:249], s[92:93], 0, v[250:251]
	global_load_dword v250, v[248:249], off sc1

; __device__ __forceinline__ unsigned xb_ld(unsigned* p)              { return __hip_atomic_load(p, __ATOMIC_RELAXED, __HIP_MEMORY_SCOPE_AGENT); }
; #define XB_SPIN(cond, bar) do { unsigned _sp = 0; while (cond) { __builtin_amdgcn_s_sleep(1); \
;     if ((++_sp & 255u) == 0u) { if (xb_ld(&(bar)[XB_TMO])) break; if (_sp > XB_SPIN_CAP) { atomicAdd(&(bar)[XB_TMO], 1u); break; } } } } while (0)
; __device__ __forceinline__ void xcd_barrier(const XcdBarrier& b) {
;     ...
;         XB_SPIN((int)(xb_ld(&bar[XB_TOP]) - target) < 0, bar);
.LBB0_104:
	s_cmp_eq_u32 s100, 0
	s_cbranch_scc1 .Lp1_skip
	v_readlane_b32 s0, v254, 14
	s_nop 3
	s_cmp_eq_u32 s0, 3
	s_cbranch_scc1 .Lp1_skip
	s_mov_b32 s100, 0
	s_cmp_lg_u32 s95, 0
	s_cbranch_scc1 .Lp1_all
	s_mov_b64 s[0:1], exec
	s_mov_b64 exec, 1
	s_waitcnt vmcnt(0)
	v_readfirstlane_b32 vcc_lo, v250
	s_sub_i32 vcc_lo, vcc_lo, s101
	s_cmp_lt_i32 vcc_lo, 0
	s_cbranch_scc0 .Lp1_done
	v_readlane_b32 vcc_lo, v253, 24
	v_mov_b32_e32 v251, 0
	s_nop 1
	s_and_b32 vcc_lo, vcc_lo, 0x700
	v_mov_b32_e32 v250, vcc_lo
	v_add_u32_e32 v250, 0x3400, v250
	s_mov_b32 vcc_hi, 0
	v_lshl_add_u64 v[248:249], s[92:93], 0, v[250:251]

; __device__ __forceinline__ unsigned xb_ld(unsigned* p)              { return __hip_atomic_load(p, __ATOMIC_RELAXED, __HIP_MEMORY_SCOPE_AGENT); }
; #define XB_SPIN(cond, bar) do { unsigned _sp = 0; while (cond) { __builtin_amdgcn_s_sleep(1); \
;     if ((++_sp & 255u) == 0u) { if (xb_ld(&(bar)[XB_TMO])) break; if (_sp > XB_SPIN_CAP) { atomicAdd(&(bar)[XB_TMO], 1u); break; } } } } while (0)
; __device__ __forceinline__ void xcd_barrier(const XcdBarrier& b) {
;     ...
;         XB_SPIN((int)(xb_ld(&bar[XB_TOP]) - target) < 0, bar);
.LBB0_261:
	s_cmp_eq_u32 s100, 0
	s_cbranch_scc1 .Lp2_skip
	s_mov_b32 s100, 0
	v_readlane_b32 vcc_lo, v253, 35
	s_nop 3
	s_cmp_lg_u32 vcc_lo, 0
	s_cbranch_scc1 .Lp2_all
	s_mov_b64 exec, 1
	s_waitcnt vmcnt(0)
	v_readfirstlane_b32 vcc_lo, v250
	s_sub_i32 vcc_lo, vcc_lo, s101
	s_cmp_lt_i32 vcc_lo, 0
	s_cbranch_scc0 .Lp2_done
	v_readlane_b32 vcc_lo, v253, 24
	v_mov_b32_e32 v251, 0
	s_nop 1
	s_and_b32 vcc_lo, vcc_lo, 0x700
	v_mov_b32_e32 v250, vcc_lo
	v_add_u32_e32 v250, 0x3400, v250
	v_readlane_b32 vcc_lo, v253, 33
	v_readlane_b32 vcc_hi, v253, 34
	s_nop 1
	v_lshl_add_u64 v[248:249], vcc, 0, v[250:251]
	s_mov_b32 vcc_hi, 0

; __device__ __forceinline__ unsigned xb_add(unsigned* p, unsigned v) { return __hip_atomic_fetch_add(p, v, __ATOMIC_RELAXED, __HIP_MEMORY_SCOPE_AGENT); }
; __device__ __forceinline__ void xcd_barrier(const XcdBarrier& b) {
;     ...
;         unsigned nloc = b.st[0], nx = b.st[1];
;         if (nloc == 0u) { xcd_barrier_complete(bar, b.x, nloc, nx); b.st[0] = nloc; b.st[1] = nx; }
;         const unsigned target = b.st[2] + nx;
;         __builtin_amdgcn_fence(__ATOMIC_ACQUIRE, "agent");
;         const unsigned old = xb_add(&bar[XB_XSUB(b.x)], 1u);
;         const unsigned gen = old / nloc;
;         if (old + 1u == (gen + 1u) * nloc) {
;             __builtin_amdgcn_fence(__ATOMIC_RELEASE, "agent");
;             asm volatile("s_waitcnt vmcnt(0)" ::: "memory");
;             (void)xb_add(&bar[XB_TOP], 1u);
;         }
.LBB0_788:
	v_readlane_b32 s4, v253, 29
	s_nop 1
	v_mov_b32_e32 v2, s4
	v_readlane_b32 s4, v253, 24
	s_add_u32 s4, s8, s4
	s_addc_u32 s5, s9, 0
	v_mov_b32_e32 v3, s4
	v_add_co_u32_e32 v4, vcc, 0x1000, v3
	v_mov_b32_e32 v3, s5
	s_nop 0
	v_addc_co_u32_e32 v5, vcc, 0, v3, vcc
	ds_read_b32 v2, v2
	s_waitcnt vmcnt(0) lgkmcnt(0)
	flat_atomic_add v3, v[4:5], v226 offset:1024 sc0
	v_cvt_f32_u32_e32 v4, v0
	v_sub_u32_e32 v5, 0, v0
	v_rcp_iflag_f32_e32 v4, v4
	s_nop 0
	v_mul_f32_e32 v4, 0x4f7ffffe, v4
	v_cvt_u32_f32_e32 v4, v4
	v_mul_lo_u32 v5, v5, v4
	v_mul_hi_u32 v5, v4, v5
	v_add_u32_e32 v4, v4, v5
	s_waitcnt vmcnt(0) lgkmcnt(0)
	v_mul_hi_u32 v4, v3, v4
	v_mul_lo_u32 v5, v4, v0
	v_sub_u32_e32 v5, v3, v5
	v_cmp_ge_u32_e32 vcc, v5, v0
	v_add_u32_e32 v6, 1, v4
	v_add_u32_e32 v3, 1, v3
	v_cndmask_b32_e32 v4, v4, v6, vcc
	v_sub_u32_e32 v6, v5, v0
	v_cndmask_b32_e32 v5, v5, v6, vcc
	v_cmp_ge_u32_e32 vcc, v5, v0
	v_add_u32_e32 v5, 1, v4
	s_nop 0
	v_cndmask_b32_e32 v4, v4, v5, vcc
	v_mad_u64_u32 v[4:5], s[4:5], v0, v4, v[0:1]
	v_cmp_eq_u32_e32 vcc, v3, v4
	s_and_saveexec_b64 s[12:13], vcc
	s_cbranch_execz .LBB0_790
	v_mov_b32_e32 v0, s8
	v_add_co_u32_e32 v4, vcc, 0x3000, v0
	v_mov_b32_e32 v0, s9
	v_addc_co_u32_e32 v5, vcc, 0, v0, vcc
	flat_atomic_add v[4:5], v226 offset:1024
	flat_atomic_add v[4:5], v226 offset:1280
	flat_atomic_add v[4:5], v226 offset:1536
	flat_atomic_add v[4:5], v226 offset:1792
	flat_atomic_add v[4:5], v226 offset:2048
	flat_atomic_add v[4:5], v226 offset:2304
	flat_atomic_add v[4:5], v226 offset:2560
	flat_atomic_add v[4:5], v226 offset:2816
